# same as previous; the global-scope XCC count is restored from the census value instead of a constant
# baseline (speedup 1.0000x reference)
; #define LAS __attribute__((address_space(3)))
; #define STEP_BEGIN(idx, flag) if (lo <= (idx) && (idx) < hi) { for (int rep_ = 0; rep_ < (((REPEAT_MASK) & (flag)) ? 2 : 1); ++rep_) { if (prev) xcd_barrier(bar); prev = true; int lane = lane_k, wave = wave_k; size_t wz_ = 0; asm volatile("" : "+v"(lane), "+s"(wave), "+s"(wz_)); unsigned char* ws = ws_k + wz_;     const int gw = blockIdx.x * 8 + wave; (void)gw; (void)lane;
; __device__ __forceinline__ void xcd_barrier(const XcdBarrier& b) {
;     ...
;         unsigned* bar = b.bar;
;         __builtin_amdgcn_s_waitcnt(0);
;         unsigned nloc = b.st[0], nx = b.st[1];
;         if (nloc == 0u) { xcd_barrier_complete(bar, b.x, nloc, nx); b.st[0] = nloc; b.st[1] = nx; }
; __global__ void __launch_bounds__(512, 2) k_mega(MegaArgs a) {
;     ...
;             STEP_BEGIN(base + 0, F_FFN_IN) { pg8::EpiSwiglu E{H, FFN}; run_gemm(lds, XB, (const bf16_t*)(ws + WS_WF_FFN_IN + lj * SZ_FFN_IN), MT, 2 * FFN, DM, E);
;                 if (gridDim.x == 256 && blockIdx.x >= 128 && rep_ == 0) {
;                     int g_lo, g_hi; sched_tail(l, kind == 3 ? 1 : 0, g_lo, g_hi);
;                     convert_stream(a, g_lo, g_hi, (blockIdx.x - 128) * 8 + wave, 1024, (LAS float*)(lds + wave * 8448), lane); }
;             } STEP_END
.LBB11_446:
	s_or_b64 exec, exec, s[4:5]
	s_waitcnt lgkmcnt(0)
	s_barrier
	s_cmp_lg_u32 s100, 1
	s_cbranch_scc1 .Lsg_ffn
	v_readlane_b32 s101, v249, 0
	s_and_b32 s101, s101, 6
	s_lshl_b32 s101, s101, 8
	s_addk_i32 s101, 0x400
	v_readlane_b32 s100, v250, 49
	s_sub_u32 s100, s100, s101
	v_writelane_b32 v250, s100, 49
	s_nop 1
	v_readlane_b32 s100, v250, 50
	s_subb_u32 s100, s100, 0
	v_writelane_b32 v250, s100, 50
	s_nop 1
	v_readlane_b32 s100, v250, 51
	s_sub_u32 s100, s100, s101
	v_writelane_b32 v250, s100, 51
	s_nop 1
	v_readlane_b32 s100, v250, 52
	s_subb_u32 s100, s100, 0
	v_writelane_b32 v250, s100, 52
	s_nop 1
	v_readlane_b32 s100, v252, 11
	s_nop 3
	v_mov_b32_e32 v1, s100
	v_readlane_b32 s100, v255, 12
	s_nop 3
	v_mov_b32_e32 v2, s100
	ds_write_b32 v1, v2
	s_waitcnt lgkmcnt(0)
	s_mov_b32 s100, 4

; #define LAS __attribute__((address_space(3)))
; #define STEP_BEGIN(idx, flag) if (lo <= (idx) && (idx) < hi) { for (int rep_ = 0; rep_ < (((REPEAT_MASK) & (flag)) ? 2 : 1); ++rep_) { if (prev) xcd_barrier(bar); prev = true; int lane = lane_k, wave = wave_k; size_t wz_ = 0; asm volatile("" : "+v"(lane), "+s"(wave), "+s"(wz_)); unsigned char* ws = ws_k + wz_;     const int gw = blockIdx.x * 8 + wave; (void)gw; (void)lane;
; __device__ __forceinline__ void xcd_barrier(const XcdBarrier& b) {
;     ...
;         unsigned* bar = b.bar;
;         __builtin_amdgcn_s_waitcnt(0);
;         unsigned nloc = b.st[0], nx = b.st[1];
;         if (nloc == 0u) { xcd_barrier_complete(bar, b.x, nloc, nx); b.st[0] = nloc; b.st[1] = nx; }
; __global__ void __launch_bounds__(512, 2) k_mega(MegaArgs a) {
;     ...
;             STEP_BEGIN(base + 0, F_XQ) { pg8::EpiBf16 E{XQ, 512}; run_gemm(lds, XB, (const bf16_t*)(ws + WS_W_XQ + l * SZ_XQ), MT, 512, DM, E);
;                 if (gridDim.x == 256 && blockIdx.x >= 64 && rep_ == 0) {
;                     const int xlo = l == 0 ? 12 : (l == 1 ? 20 : (l == 2 ? 29 : 37)), xhi = xlo + 2;
;                     convert_stream(a, xlo, xhi, (blockIdx.x - 64) * 8 + wave, 1536, (LAS float*)(lds + wave * 8448), lane); }
;             } STEP_END
.LBB11_624:
	s_or_b64 exec, exec, s[2:3]
	s_waitcnt lgkmcnt(0)
	s_barrier
	s_cmp_lg_u32 s100, 1
	s_cbranch_scc1 .Lsg_xq
	v_readlane_b32 s101, v249, 0
	s_and_b32 s101, s101, 6
	s_lshl_b32 s101, s101, 8
	s_addk_i32 s101, 0x400
	v_readlane_b32 s100, v250, 49
	s_sub_u32 s100, s100, s101
	v_writelane_b32 v250, s100, 49
	s_nop 1
	v_readlane_b32 s100, v250, 50
	s_subb_u32 s100, s100, 0
	v_writelane_b32 v250, s100, 50
	s_nop 1
	v_readlane_b32 s100, v250, 51
	s_sub_u32 s100, s100, s101
	v_writelane_b32 v250, s100, 51
	s_nop 1
	v_readlane_b32 s100, v250, 52
	s_subb_u32 s100, s100, 0
	v_writelane_b32 v250, s100, 52
	s_nop 1
	v_readlane_b32 s100, v252, 11
	s_nop 3
	v_mov_b32_e32 v1, s100
	v_readlane_b32 s100, v255, 12
	s_nop 3
	v_mov_b32_e32 v2, s100
	ds_write_b32 v1, v2
	s_waitcnt lgkmcnt(0)
	s_mov_b32 s100, 4

; #define STEP_BEGIN(idx, flag) if (lo <= (idx) && (idx) < hi) { for (int rep_ = 0; rep_ < (((REPEAT_MASK) & (flag)) ? 2 : 1); ++rep_) { if (prev) xcd_barrier(bar); prev = true; int lane = lane_k, wave = wave_k; size_t wz_ = 0; asm volatile("" : "+v"(lane), "+s"(wave), "+s"(wz_)); unsigned char* ws = ws_k + wz_;     const int gw = blockIdx.x * 8 + wave; (void)gw; (void)lane;
; __device__ __forceinline__ void xcd_barrier(const XcdBarrier& b) {
;     ...
;         unsigned* bar = b.bar;
;         __builtin_amdgcn_s_waitcnt(0);
;         unsigned nloc = b.st[0], nx = b.st[1];
;         if (nloc == 0u) { xcd_barrier_complete(bar, b.x, nloc, nx); b.st[0] = nloc; b.st[1] = nx; }
; __global__ void __launch_bounds__(512, 2) k_mega(MegaArgs a) {
;     ...
;             STEP_BEGIN(base + 5, F_OUT) {
;                 unsigned* ctl = (unsigned*)(ws + WS_CTL);
;     ...
;                 pg8::EpiLnFused E{(sb == 0) ? a.in[0] : (const float*)nullptr, XB, (sb == 15) ? a.out : nullptr, DM, lng, lnb, ALPHA, ocs, st};
;                 run_gemm_fused(lds, oA, oB, MT, DM, oK, E);
;             } STEP_END
.LBB11_1879:
	s_or_b64 exec, exec, s[2:3]
	s_waitcnt lgkmcnt(0)
	s_barrier
	s_cmp_eq_u32 s100, 4
	s_cbranch_scc1 .Ldo_out
	s_cmp_lg_u32 s100, 0
	s_cbranch_scc1 .Lsp_out
	v_readlane_b32 s100, v249, 31
	v_readlane_b32 s101, v249, 32
	s_add_u32 s100, s100, 0x8000
	s_addc_u32 s101, s101, 0
	v_mbcnt_lo_u32_b32 v1, -1, 0
	v_mbcnt_hi_u32_b32 v1, -1, v1
	v_lshlrev_b32_e32 v1, 2, v1
	global_load_dword v2, v1, s[100:101] sc1
	s_waitcnt vmcnt(0)
	v_bcnt_u32_b32 v1, v2, 0
	v_cmp_lt_u32_e32 vcc, 1, v1
	s_nop 1
	v_readlane_b32 s100, v252, 11
	s_nop 3
	v_mov_b32_e32 v1, s100
	ds_read_b32 v2, v1
	s_waitcnt lgkmcnt(0)
	v_readfirstlane_b32 s100, v2
	s_nop 3
	v_writelane_b32 v255, s100, 12
	s_barrier
	s_cmp_lg_u64 vcc, 0
	s_mov_b32 s100, 2
	s_cbranch_scc1 .Lsp_out
